# speedup vs baseline: 1.0024x; 1.0000x over previous
; __device__ __forceinline__ int otid() { int t = threadIdx.x; asm volatile("" : "+v"(t)); return t; }
; __device__ void phase_attn(const Params& p, int layer, unsigned char* smem) {
;     ...
;     for (;;) {
;         int it;
;         if (nxt >= 0) { it = nxt; nxt = -1; }
;         else {
;             if (nxt == -1 && otid() == 0) *slot = (int)__hip_atomic_fetch_add(ctr, 1u, __ATOMIC_RELAXED, __HIP_MEMORY_SCOPE_AGENT);
;             nxt = -1;
;             __syncthreads();
;             const int t = __builtin_amdgcn_readfirstlane(*slot);
;             __syncthreads();
;             if (t >= 1792) break;
;             if (t < 1024) it = t; else { it = 1024 + (t - 1024) * 2; nxt = it + 1; }
.LBB0_392:
	s_waitcnt lgkmcnt(0)
	s_barrier
	ds_read_b32 v0, v207
	s_waitcnt lgkmcnt(0)
	s_barrier
	v_readfirstlane_b32 s6, v0
	s_cmpk_lt_i32 s6, 0x780
	s_cselect_b64 s[4:5], -1, 0
	s_lshl_b32 s7, s6, 1
	s_add_i32 s8, s7, 0xfffffc00
	s_addk_i32 s7, 0xfc01
	s_cmpk_lt_i32 s6, 0x400
	s_cselect_b32 s28, s6, s8
	s_cselect_b32 s99, -1, s7
	s_cmpk_lt_i32 s6, 0x680
	s_cbranch_scc1 .Lmy_tk_pair
	s_add_i32 s28, s6, 0x280
	s_mov_b32 s99, -1
.Lmy_tk_pair:
	s_and_b64 vcc, exec, s[4:5]
	s_cbranch_vccz .LBB0_384
	s_branch .LBB0_394
